# attention unit prologue: one memory round trip (K/V tile loads no longer wait for Q/table loads); dtype comment
# speedup vs baseline: 1.0017x; 1.0017x over previous
.LBB0_578:
	s_or_b64 exec, exec, s[68:69]
	s_mov_b32 s41, s53
	s_lshl_b64 s[68:69], s[40:41], 10
	s_add_u32 s37, s46, s68
	s_addc_u32 s48, s47, s69
	s_lshl_b32 s3, s22, 1
	s_add_u32 s37, s37, s3
	s_addc_u32 s48, s48, 0
	s_add_u32 s60, s37, 0xab00000
	s_addc_u32 s61, s48, 0
	v_and_b32_e32 v27, 15, v18
	v_lshlrev_b64 v[32:33], 10, v[22:23]
	s_lshl_b32 s52, s22, 16
	v_lshlrev_b32_e32 v176, 4, v27
	v_lshl_add_u64 v[32:33], s[60:61], 0, v[32:33]
	s_add_u32 s37, s42, s52
	v_lshl_add_u64 v[36:37], v[32:33], 0, v[176:177]
	s_mov_b32 s7, 0x8000
	s_addc_u32 s48, s43, 0
	s_lshl_b64 s[70:71], s[40:41], 1
	v_ashrrev_i32_e32 v34, 3, v18
	v_lshl_add_u64 v[30:31], s[60:61], 0, v[16:17]
	v_add_co_u32_e64 v32, s[40:41], s7, v36
	s_add_u32 s62, s37, s70
	v_lshl_add_u64 v[30:31], v[30:31], 0, v[176:177]
	v_addc_co_u32_e64 v33, s[40:41], 0, v37, s[40:41]
	v_ashrrev_i32_e32 v35, 31, v34
	s_addc_u32 s63, s48, s71
	v_and_b32_e32 v29, 7, v18
	flat_load_dwordx4 v[96:99], v[30:31]
	flat_load_dwordx4 v[100:103], v[32:33]
	v_lshlrev_b64 v[32:33], 16, v[34:35]
	v_lshl_add_u64 v[38:39], s[62:63], 0, v[32:33]
	v_lshlrev_b32_e32 v30, 4, v29
	v_mov_b32_e32 v31, v177
	v_lshl_add_u64 v[38:39], v[38:39], 0, v[30:31]
	s_mov_b32 s7, 0xcb00000
	s_mov_b64 s[14:15], 0xcb00000
	v_add_co_u32_e64 v42, s[40:41], s7, v38
	v_lshl_add_u64 v[40:41], v[38:39], 0, s[14:15]
	s_nop 0
	v_addc_co_u32_e64 v43, s[40:41], 0, v39, s[40:41]
	s_mov_b64 s[14:15], 0xcf00000
	s_mov_b32 s7, 0xcf00000
	v_lshl_add_u64 v[44:45], v[38:39], 0, s[14:15]
	v_add_co_u32_e64 v38, s[40:41], s7, v38
	v_readlane_b32 s7, v255, 23
	s_nop 0
	v_addc_co_u32_e64 v39, s[40:41], 0, v39, s[40:41]
	v_add_co_u32_e64 v46, s[40:41], s9, v36
	s_nop 1
	v_addc_co_u32_e64 v47, s[40:41], 0, v37, s[40:41]
	v_add_co_u32_e64 v36, s[40:41], s10, v36
	s_nop 1
	v_addc_co_u32_e64 v37, s[40:41], 0, v37, s[40:41]
	flat_load_dwordx4 v[104:107], v[46:47]
	flat_load_dwordx4 v[108:111], v[36:37]
	flat_load_dwordx4 v[120:123], v[42:43]
	flat_load_dwordx4 v[112:115], v[40:41] offset:128
	flat_load_dwordx4 v[124:127], v[38:39]
	flat_load_dwordx4 v[116:119], v[44:45] offset:128
	v_add_u32_e32 v36, s7, v20
	v_mul_lo_u32 v20, v22, s12
	v_add_u32_e32 v22, v36, v20
	s_waitcnt vmcnt(0) lgkmcnt(0)
	v_lshlrev_b32_e32 v84, 2, v18
	v_add_u32_e32 v84, 0x1ac00, v84
	ds_write_b32 v84, v88
	v_lshlrev_b32_e32 v85, 2, v85
	v_add_u32_e32 v85, 0x1ac00, v85
	ds_write_b32 v85, v89
	ds_write_b128 v22, v[4:7]
	v_mad_u64_u32 v[4:5], s[40:41], v24, s12, v[36:37]
	ds_write_b128 v4, v[0:3]
	v_mad_u64_u32 v[0:1], s[40:41], v26, s12, v[36:37]
	ds_write_b128 v0, v[12:15]
	v_mad_u64_u32 v[0:1], s[40:41], v28, s12, v[36:37]
	ds_write_b128 v0, v[8:11]
	v_lshl_add_u32 v0, v18, 2, 0
	v_add_u32_e32 v1, 0x11800, v0
	ds_write_b32 v1, v21
	s_and_saveexec_b64 s[40:41], vcc
	ds_write_b32 v1, v25 offset:2048
	s_or_b64 exec, exec, s[40:41]
	s_and_saveexec_b64 s[40:41], s[0:1]
	v_add_u32_e32 v0, 0x1a900, v0
	ds_write_b32 v0, v19
	s_or_b64 exec, exec, s[40:41]
	s_ashr_i32 s60, s58, 8
	s_lshl_b32 s0, s60, 7
	s_bfe_u32 s61, s58, 0x20006
	s_add_i32 s1, s0, 0
	v_and_b32_e32 v2, 31, v18
	s_lshl_b32 s37, s61, 5
	s_add_i32 s1, s1, 0x12100
	v_or_b32_e32 v1, s37, v2
	v_mov_b32_e32 v3, s1
	v_lshlrev_b32_e32 v0, 3, v18
	v_mad_u32_u24 v3, v1, s12, v3
	v_add_u32_e32 v1, 0, v20
	s_movk_i32 s1, 0x90
	v_and_b32_e32 v0, 8, v0
	v_add_u32_e32 v239, v1, v176
	v_mul_lo_u32 v1, v34, s1
	v_and_or_b32 v0, v30, s8, v0
	v_add_u32_e32 v1, 0, v1
	v_add_u32_e32 v240, v1, v0
	s_mul_i32 s1, s60, 0x410
	v_mad_u32_u24 v0, v2, s12, 0
	s_add_i32 s62, s1, 0
	s_or_b32 s72, s37, s73
	v_add_u32_e32 v4, s0, v0
	s_lshl_b32 s0, s77, 4
	s_lshr_b32 s59, s58, 6
	s_add_i32 s62, s62, 0x11800
	s_add_i32 s63, s72, 0x9f
	s_addk_i32 s72, 0x5f
	s_and_b32 s0, s0, 0x300
	v_bfe_u32 v236, v18, 5, 1
	v_lshlrev_b32_e32 v1, 7, v2
	s_add_u32 s0, s0, s68
	v_lshlrev_b32_e32 v237, 4, v236
	v_sub_u32_e32 v0, v0, v1
	s_addc_u32 s1, 0, s69
	v_add_u32_e32 v243, v0, v237
	v_lshl_add_u64 v[0:1], s[0:1], 0, v[16:17]
	v_lshl_add_u64 v[0:1], v[0:1], 0, v[176:177]
	v_lshl_add_u64 v[0:1], s[46:47], 0, v[0:1]
	s_mov_b64 s[0:1], 0xab38000
	v_lshl_add_u64 v[190:191], v[0:1], 0, s[0:1]
	v_lshl_add_u64 v[0:1], s[52:53], 0, v[32:33]
	v_mov_b32_e32 v31, v177
	s_add_u32 s0, s42, s70
	v_lshl_add_u64 v[0:1], v[0:1], 0, v[30:31]
	s_addc_u32 s1, s43, s71
	v_lshlrev_b32_e32 v235, 2, v236
	v_lshl_add_u64 v[0:1], s[0:1], 0, v[0:1]
	s_mov_b64 s[0:1], 0xcf00180
	v_lshl_add_u64 v[192:193], v[0:1], 0, s[0:1]
	v_sub_u32_e32 v0, v235, v2
	v_subrev_u32_e32 v0, s37, v0
	s_add_i32 s0, s37, s73
	v_mov_b32_e32 v248, 0
	v_lshlrev_b32_e32 v233, 3, v27
	v_and_b32_e32 v234, 63, v18
	v_add_u32_e32 v241, 0x8800, v240
	v_add_u32_e32 v242, 0xa800, v240
	v_mul_u32_u24_e32 v238, 0x110, v2
	v_add_u32_e32 v244, 0xd000, v243
	v_subrev_u32_e32 v245, s73, v0
	s_mov_b32 s22, 0
	s_sub_i32 s46, 0, s0
	v_add_u32_e32 v246, v4, v237
	v_add_u32_e32 v247, v3, v237
	s_mov_b32 s47, 0
	v_mov_b32_e32 v0, 0
	v_mov_b32_e32 v1, v248
	v_mov_b32_e32 v2, v248
	v_mov_b32_e32 v3, v248
	v_mov_b32_e32 v4, v248
	v_mov_b32_e32 v5, v248
	v_mov_b32_e32 v6, v248
	v_mov_b32_e32 v7, v248
	v_mov_b32_e32 v8, v248
	v_mov_b32_e32 v9, v248
	v_mov_b32_e32 v10, v248
	v_mov_b32_e32 v11, v248
	v_mov_b32_e32 v12, v248
	v_mov_b32_e32 v13, v248
	v_mov_b32_e32 v14, v248
	v_mov_b32_e32 v15, v248
	v_mov_b32_e32 v16, 0
	v_mov_b32_e32 v17, v248
	v_mov_b32_e32 v18, v248
	v_mov_b32_e32 v19, v248
	v_mov_b32_e32 v20, v248
	v_mov_b32_e32 v21, v248
	v_mov_b32_e32 v22, v248
	v_mov_b32_e32 v23, v248
	v_mov_b32_e32 v24, v248
	v_mov_b32_e32 v25, v248
	v_mov_b32_e32 v26, v248
	v_mov_b32_e32 v27, v248
	v_mov_b32_e32 v28, v248
	v_mov_b32_e32 v29, v248
	v_mov_b32_e32 v30, v248
	v_mov_b32_e32 v31, v248
	v_mov_b32_e32 v32, 0
	v_mov_b32_e32 v33, v248
	v_mov_b32_e32 v34, v248
	v_mov_b32_e32 v35, v248
	v_mov_b32_e32 v36, v248
	v_mov_b32_e32 v37, v248
	v_mov_b32_e32 v38, v248
	v_mov_b32_e32 v39, v248
	v_mov_b32_e32 v40, v248
	v_mov_b32_e32 v41, v248
	v_mov_b32_e32 v42, v248
	v_mov_b32_e32 v43, v248
	v_mov_b32_e32 v44, v248
	v_mov_b32_e32 v45, v248
	v_mov_b32_e32 v46, v248
	v_mov_b32_e32 v47, v248
	v_mov_b32_e32 v48, 0
	v_mov_b32_e32 v49, v248
	v_mov_b32_e32 v50, v248
	v_mov_b32_e32 v51, v248
	v_mov_b32_e32 v52, v248
	v_mov_b32_e32 v53, v248
	v_mov_b32_e32 v54, v248
	v_mov_b32_e32 v55, v248
	v_mov_b32_e32 v56, v248
	v_mov_b32_e32 v57, v248
	v_mov_b32_e32 v58, v248
	v_mov_b32_e32 v59, v248
	v_mov_b32_e32 v60, v248
	v_mov_b32_e32 v61, v248
	v_mov_b32_e32 v62, v248
	v_mov_b32_e32 v63, v248
	ds_write_b128 v239, v[96:99]
	ds_write_b128 v239, v[100:103] offset:8704
	ds_write2_b64 v241, v[120:121], v[122:123] offset1:2
	ds_write2_b64 v242, v[124:125], v[126:127] offset0:128 offset1:130
	s_waitcnt lgkmcnt(0)
	s_barrier
	ds_read_b128 v[222:225], v247
	ds_read_b128 v[218:221], v247 offset:32
	ds_read_b128 v[214:217], v247 offset:64
	ds_read_b128 v[210:213], v247 offset:96
	s_mov_b32 s100, -1
	s_branch .LBB0_584

.LBB0_617:
	s_or_b64 exec, exec, s[70:71]
	s_ashr_i32 s41, s40, 31
	s_lshl_b64 s[70:71], s[40:41], 10
	s_add_u32 s37, s42, s70
	s_addc_u32 s48, s43, s71
	s_lshl_b32 s3, s22, 1
	s_add_u32 s37, s37, s3
	s_addc_u32 s48, s48, 0
	s_add_u32 s60, s37, 0xab00000
	s_addc_u32 s61, s48, 0
	v_and_b32_e32 v27, 15, v18
	v_lshlrev_b64 v[32:33], 10, v[22:23]
	s_lshl_b32 s52, s22, 16
	v_lshlrev_b32_e32 v176, 4, v27
	v_lshl_add_u64 v[32:33], s[60:61], 0, v[32:33]
	s_add_u32 s37, s46, s52
	v_lshl_add_u64 v[36:37], v[32:33], 0, v[176:177]
	s_mov_b32 s7, 0x8000
	s_addc_u32 s48, s47, 0
	s_lshl_b64 s[72:73], s[40:41], 1
	v_ashrrev_i32_e32 v34, 3, v18
	v_lshl_add_u64 v[30:31], s[60:61], 0, v[16:17]
	v_add_co_u32_e64 v32, s[40:41], s7, v36
	s_add_u32 s62, s37, s72
	v_lshl_add_u64 v[30:31], v[30:31], 0, v[176:177]
	v_addc_co_u32_e64 v33, s[40:41], 0, v37, s[40:41]
	v_ashrrev_i32_e32 v35, 31, v34
	s_addc_u32 s63, s48, s73
	v_and_b32_e32 v29, 7, v18
	global_load_dwordx4 v[96:99], v[30:31], off
	global_load_dwordx4 v[100:103], v[32:33], off
	v_lshlrev_b64 v[32:33], 16, v[34:35]
	v_lshl_add_u64 v[38:39], s[62:63], 0, v[32:33]
	v_lshlrev_b32_e32 v30, 4, v29
	v_mov_b32_e32 v31, v177
	v_lshl_add_u64 v[38:39], v[38:39], 0, v[30:31]
	s_mov_b32 s7, 0xcb00000
	s_mov_b64 s[14:15], 0xcb00000
	v_add_co_u32_e64 v42, s[40:41], s7, v38
	v_lshl_add_u64 v[40:41], v[38:39], 0, s[14:15]
	s_nop 0
	v_addc_co_u32_e64 v43, s[40:41], 0, v39, s[40:41]
	s_mov_b64 s[14:15], 0xcf00000
	s_mov_b32 s7, 0xcf00000
	v_lshl_add_u64 v[44:45], v[38:39], 0, s[14:15]
	v_add_co_u32_e64 v38, s[40:41], s7, v38
	v_readlane_b32 s7, v255, 23
	s_nop 0
	v_addc_co_u32_e64 v39, s[40:41], 0, v39, s[40:41]
	v_add_co_u32_e64 v46, s[40:41], s9, v36
	s_nop 1
	v_addc_co_u32_e64 v47, s[40:41], 0, v37, s[40:41]
	v_add_co_u32_e64 v36, s[40:41], s10, v36
	s_nop 1
	v_addc_co_u32_e64 v37, s[40:41], 0, v37, s[40:41]
	global_load_dwordx4 v[104:107], v[46:47], off
	global_load_dwordx4 v[108:111], v[36:37], off
	global_load_dwordx4 v[120:123], v[42:43], off
	global_load_dwordx4 v[112:115], v[40:41], off offset:128
	global_load_dwordx4 v[124:127], v[38:39], off
	global_load_dwordx4 v[116:119], v[44:45], off offset:128
	v_add_u32_e32 v36, s7, v20
	v_mul_lo_u32 v20, v22, s12
	v_add_u32_e32 v22, v36, v20
	s_waitcnt vmcnt(0) lgkmcnt(0)
	v_lshlrev_b32_e32 v84, 2, v18
	v_add_u32_e32 v84, 0x1ac00, v84
	ds_write_b32 v84, v88
	v_lshlrev_b32_e32 v85, 2, v85
	v_add_u32_e32 v85, 0x1ac00, v85
	ds_write_b32 v85, v89
	ds_write_b128 v22, v[4:7]
	v_mad_u64_u32 v[4:5], s[40:41], v24, s12, v[36:37]
	ds_write_b128 v4, v[0:3]
	v_mad_u64_u32 v[0:1], s[40:41], v26, s12, v[36:37]
	ds_write_b128 v0, v[12:15]
	v_mad_u64_u32 v[0:1], s[40:41], v28, s12, v[36:37]
	ds_write_b128 v0, v[8:11]
	v_lshl_add_u32 v0, v18, 2, 0
	v_add_u32_e32 v1, 0x11800, v0
	ds_write_b32 v1, v21
	s_and_saveexec_b64 s[40:41], vcc
	ds_write_b32 v1, v25 offset:2048
	s_or_b64 exec, exec, s[40:41]
	s_and_saveexec_b64 s[40:41], s[0:1]
	v_add_u32_e32 v0, 0x1a900, v0
	ds_write_b32 v0, v19
	s_or_b64 exec, exec, s[40:41]
	s_ashr_i32 s60, s58, 8
	s_lshl_b32 s40, s60, 7
	s_bfe_u32 s61, s58, 0x20006
	s_add_i32 s0, s40, 0
	s_lshr_b32 s59, s58, 6
	v_and_b32_e32 v2, 31, v18
	s_lshl_b32 s37, s61, 5
	s_add_i32 s0, s0, 0x12100
	v_or_b32_e32 v1, s37, v2
	v_mov_b32_e32 v3, s0
	s_and_b64 s[0:1], s[68:69], exec
	v_lshlrev_b32_e32 v0, 3, v18
	v_mad_u32_u24 v3, v1, s12, v3
	v_add_u32_e32 v1, 0, v20
	s_movk_i32 s0, 0x90
	v_and_b32_e32 v0, 8, v0
	v_add_u32_e32 v239, v1, v176
	v_mul_lo_u32 v1, v34, s0
	v_and_or_b32 v0, v30, s8, v0
	v_add_u32_e32 v1, 0, v1
	s_mul_i32 s0, s60, 0x410
	v_bfe_u32 v236, v18, 5, 1
	s_cselect_b32 s62, 32, 64
	v_add_u32_e32 v240, v1, v0
	s_add_i32 s63, s0, 0
	s_or_b32 s69, s37, s78
	v_mad_u32_u24 v0, v2, s12, 0
	v_lshlrev_b32_e32 v1, 7, v2
	v_lshlrev_b32_e32 v237, 4, v236
	s_add_i32 s63, s63, 0x11800
	v_add_u32_e32 v4, s40, v0
	v_sub_u32_e32 v0, v0, v1
	s_add_i32 s68, s69, 0x9f
	s_addk_i32 s69, 0x5f
	v_add_u32_e32 v243, v0, v237
	v_lshl_add_u64 v[0:1], s[52:53], 0, v[32:33]
	v_mov_b32_e32 v31, v177
	s_add_u32 s0, s46, s72
	v_lshl_add_u64 v[0:1], v[0:1], 0, v[30:31]
	s_addc_u32 s1, s47, s73
	v_lshl_add_u64 v[0:1], s[0:1], 0, v[0:1]
	s_mov_b64 s[0:1], 0xcf00180
	v_lshl_add_u64 v[190:191], v[0:1], 0, s[0:1]
	s_lshl_b32 s0, s77, 3
	s_and_b32 s0, s0, 0x300
	s_add_u32 s0, s0, s70
	s_addc_u32 s1, 0, s71
	v_lshl_add_u64 v[0:1], s[0:1], 0, v[16:17]
	v_lshl_add_u64 v[0:1], v[0:1], 0, v[176:177]
	v_lshlrev_b32_e32 v235, 2, v236
	v_lshl_add_u64 v[0:1], s[42:43], 0, v[0:1]
	s_mov_b64 s[0:1], 0xab38000
	v_lshl_add_u64 v[192:193], v[0:1], 0, s[0:1]
	v_sub_u32_e32 v0, v235, v2
	v_subrev_u32_e32 v0, s37, v0
	s_add_i32 s0, s37, s78
	v_mov_b32_e32 v248, 0
	v_lshlrev_b32_e32 v233, 3, v27
	v_and_b32_e32 v234, 63, v18
	v_add_u32_e32 v241, 0x8800, v240
	v_add_u32_e32 v242, 0xa800, v240
	v_mul_u32_u24_e32 v238, 0x110, v2
	v_add_u32_e32 v244, 0xd000, v243
	s_mov_b32 s22, 3
	v_subrev_u32_e32 v245, s78, v0
	s_mov_b32 s42, 0
	s_sub_i32 s43, 0, s0
	v_add_u32_e32 v246, v4, v237
	v_add_u32_e32 v247, v3, v237
	v_mov_b32_e32 v0, 0
	v_mov_b32_e32 v1, v248
	v_mov_b32_e32 v2, v248
	v_mov_b32_e32 v3, v248
	v_mov_b32_e32 v4, v248
	v_mov_b32_e32 v5, v248
	v_mov_b32_e32 v6, v248
	v_mov_b32_e32 v7, v248
	v_mov_b32_e32 v8, v248
	v_mov_b32_e32 v9, v248
	v_mov_b32_e32 v10, v248
	v_mov_b32_e32 v11, v248
	v_mov_b32_e32 v12, v248
	v_mov_b32_e32 v13, v248
	v_mov_b32_e32 v14, v248
	v_mov_b32_e32 v15, v248
	v_mov_b32_e32 v16, 0
	v_mov_b32_e32 v17, v248
	v_mov_b32_e32 v18, v248
	v_mov_b32_e32 v19, v248
	v_mov_b32_e32 v20, v248
	v_mov_b32_e32 v21, v248
	v_mov_b32_e32 v22, v248
	v_mov_b32_e32 v23, v248
	v_mov_b32_e32 v24, v248
	v_mov_b32_e32 v25, v248
	v_mov_b32_e32 v26, v248
	v_mov_b32_e32 v27, v248
	v_mov_b32_e32 v28, v248
	v_mov_b32_e32 v29, v248
	v_mov_b32_e32 v30, v248
	v_mov_b32_e32 v31, v248
	v_mov_b32_e32 v32, 0
	v_mov_b32_e32 v33, v248
	v_mov_b32_e32 v34, v248
	v_mov_b32_e32 v35, v248
	v_mov_b32_e32 v36, v248
	v_mov_b32_e32 v37, v248
	v_mov_b32_e32 v38, v248
	v_mov_b32_e32 v39, v248
	v_mov_b32_e32 v40, v248
	v_mov_b32_e32 v41, v248
	v_mov_b32_e32 v42, v248
	v_mov_b32_e32 v43, v248
	v_mov_b32_e32 v44, v248
	v_mov_b32_e32 v45, v248
	v_mov_b32_e32 v46, v248
	v_mov_b32_e32 v47, v248
	v_mov_b32_e32 v48, 0
	v_mov_b32_e32 v49, v248
	v_mov_b32_e32 v50, v248
	v_mov_b32_e32 v51, v248
	v_mov_b32_e32 v52, v248
	v_mov_b32_e32 v53, v248
	v_mov_b32_e32 v54, v248
	v_mov_b32_e32 v55, v248
	v_mov_b32_e32 v56, v248
	v_mov_b32_e32 v57, v248
	v_mov_b32_e32 v58, v248
	v_mov_b32_e32 v59, v248
	v_mov_b32_e32 v60, v248
	v_mov_b32_e32 v61, v248
	v_mov_b32_e32 v62, v248
	v_mov_b32_e32 v63, v248
	s_waitcnt vmcnt(0)
	ds_write_b128 v239, v[96:99]
	ds_write_b128 v239, v[100:103] offset:8704
	ds_write2_b64 v241, v[120:121], v[122:123] offset1:2
	ds_write2_b64 v242, v[124:125], v[126:127] offset0:128 offset1:130
	s_waitcnt lgkmcnt(0)
	s_barrier
	ds_read_b128 v[222:225], v247
	ds_read_b128 v[218:221], v247 offset:32
	ds_read_b128 v[214:217], v247 offset:64
	ds_read_b128 v[210:213], v247 offset:96
	s_mov_b32 s100, -1
	s_branch .LBB0_623
